# attention steady loop: the +0 add closing each 32-term row sum deleted as well (sums of exponentials are positive); placement of later loops kept by padding
# speedup vs baseline: 1.0045x; 1.0005x over previous
.LBB0_563:
	v_add_u32_e32 v0, s12, v194
	ds_read_b64_tr_b16 v[168:169], v0 offset:24576
	ds_read_b64_tr_b16 v[170:171], v0 offset:25088
	s_waitcnt lgkmcnt(5)
	v_mfma_f32_32x32x16_bf16 v[112:127], v[164:167], v[144:147], v[48:63]
	v_add_f32_e32 v2, v80, v81
	v_add_f32_e32 v2, v82, v2
	v_add_f32_e32 v2, v83, v2
	v_add_f32_e32 v2, v84, v2
	v_add_f32_e32 v2, v85, v2
	v_cvt_pk_bf16_f32 v148, v80, v81
	v_cvt_pk_bf16_f32 v149, v82, v83
	ds_read_b64_tr_b16 v[164:165], v0 offset:28672
	ds_read_b64_tr_b16 v[166:167], v0 offset:29184
	s_waitcnt lgkmcnt(6)
	v_mfma_f32_32x32x16_bf16 v[96:111], v[160:163], v[144:147], v[48:63]
	v_add_f32_e32 v2, v86, v2
	v_add_f32_e32 v2, v87, v2
	v_add_f32_e32 v2, v88, v2
	v_add_f32_e32 v2, v89, v2
	v_cvt_pk_bf16_f32 v150, v84, v85
	v_cvt_pk_bf16_f32 v151, v86, v87
	ds_read_b64_tr_b16 v[6:7], v0 offset:25600
	ds_read_b64_tr_b16 v[8:9], v0 offset:26112
	s_waitcnt lgkmcnt(7)
	v_mfma_f32_32x32x16_bf16 v[112:127], v[156:159], v[136:139], v[112:127]
	v_add_f32_e32 v2, v90, v2
	v_add_f32_e32 v2, v91, v2
	v_add_f32_e32 v2, v92, v2
	v_add_f32_e32 v2, v93, v2
	v_cvt_pk_bf16_f32 v140, v88, v89
	v_cvt_pk_bf16_f32 v141, v90, v91
	ds_read_b64_tr_b16 v[80:81], v0 offset:29696
	ds_read_b64_tr_b16 v[82:83], v0 offset:30208
	s_waitcnt lgkmcnt(8)
	v_mfma_f32_32x32x16_bf16 v[96:111], v[152:155], v[136:139], v[96:111]
	v_add_f32_e32 v2, v94, v2
	v_add_f32_e32 v2, v95, v2
	v_add_f32_e32 v2, v64, v2
	v_add_f32_e32 v2, v65, v2
	v_cvt_pk_bf16_f32 v142, v92, v93
	v_cvt_pk_bf16_f32 v143, v94, v95
	ds_read_b64_tr_b16 v[84:85], v0 offset:26624
	ds_read_b64_tr_b16 v[86:87], v0 offset:27136
	v_add_f32_e32 v2, v66, v2
	v_add_f32_e32 v2, v67, v2
	v_add_f32_e32 v2, v68, v2
	v_add_f32_e32 v2, v69, v2
	v_cvt_pk_bf16_f32 v132, v64, v65
	v_cvt_pk_bf16_f32 v133, v66, v67
	ds_read_b64_tr_b16 v[64:65], v0 offset:30720
	ds_read_b64_tr_b16 v[66:67], v0 offset:31232
	v_add_f32_e32 v2, v70, v2
	v_add_f32_e32 v2, v71, v2
	v_add_f32_e32 v2, v72, v2
	v_add_f32_e32 v2, v73, v2
	v_cvt_pk_bf16_f32 v134, v68, v69
	v_cvt_pk_bf16_f32 v135, v70, v71
	ds_read_b64_tr_b16 v[10:11], v0 offset:27648
	ds_read_b64_tr_b16 v[12:13], v0 offset:28160
	v_add_f32_e32 v2, v74, v2
	v_add_f32_e32 v2, v75, v2
	v_add_f32_e32 v2, v76, v2
	v_add_f32_e32 v14, v77, v2
	v_cvt_pk_bf16_f32 v128, v72, v73
	v_cvt_pk_bf16_f32 v129, v74, v75
	ds_read_b64_tr_b16 v[2:3], v0 offset:31744
	ds_read_b64_tr_b16 v[4:5], v0 offset:32256
	v_add_f32_e32 v0, v78, v14
	v_add_f32_e32 v0, v79, v0
	v_cvt_pk_bf16_f32 v130, v76, v77
	v_cvt_pk_bf16_f32 v131, v78, v79
	v_lshl_add_u64 v[14:15], v[178:179], 0, s[50:51]
	s_add_i32 s12, s3, s75
	s_mov_b32 s13, m0
	s_mov_b32 m0, s12
	s_nop 0
	global_load_lds_dwordx4 v[14:15], off
	s_mov_b32 m0, s13
	s_mov_b32 s12, 0xfffb0000
	s_mov_b32 s13, -1
	v_lshl_add_u64 v[14:15], v[176:177], 0, s[12:13]
	s_add_i32 s12, s16, s76
	s_mov_b32 s13, m0
	s_mov_b32 m0, s12
	s_nop 0
	global_load_lds_dwordx4 v[14:15], off
	s_mov_b32 m0, s13
	v_max_f32_e32 v14, v113, v113
	v_max_f32_e32 v15, v112, v112
	v_max_f32_e32 v14, v15, v14
	v_max3_f32 v15, v114, v115, v97
	v_max3_f32 v14, v14, v96, v98
	v_max3_f32 v14, v14, v99, v116
	v_max3_f32 v15, v15, v118, v119
	v_max3_f32 v14, v14, v117, v100
	v_max3_f32 v15, v15, v102, v103
	v_max3_f32 v14, v14, v101, v120
	v_max3_f32 v15, v15, v122, v123
	v_max3_f32 v14, v14, v121, v104
	v_max3_f32 v15, v15, v106, v107
	v_max3_f32 v14, v14, v105, v124
	v_max3_f32 v15, v15, v126, v127
	v_max3_f32 v68, v14, v125, v108
	v_max3_f32 v15, v15, v110, v111
	v_add_f32_e32 v14, v196, v0
	v_max3_f32 v0, v68, v109, v15
	v_mov_b32_e32 v15, v0
	s_nop 1
	v_permlane32_swap_b32_e32 v0, v15
	v_max_f32_e32 v0, v0, v15
	v_cmp_lt_f32_e32 vcc, s58, v0
	s_cmp_lg_u64 vcc, 0
	s_cselect_b64 s[12:13], -1, 0
	s_cbranch_vccnz .LBB0_571

.LBB0_566:
	s_add_i32 s12, s16, 0x2000
	s_cmpk_lg_i32 s16, 0x4000
	s_cselect_b32 s78, s12, 0
	v_add_u32_e32 v4, s3, v194
	ds_read_b64_tr_b16 v[156:157], v4 offset:24576
	ds_read_b64_tr_b16 v[158:159], v4 offset:25088
	s_waitcnt lgkmcnt(5)
	v_mfma_f32_32x32x16_bf16 v[80:95], v[68:71], v[144:147], v[48:63]
	v_add_f32_e32 v2, v112, v113
	v_add_f32_e32 v2, v114, v2
	v_add_f32_e32 v2, v115, v2
	v_add_f32_e32 v2, v116, v2
	v_add_f32_e32 v2, v117, v2
	v_cvt_pk_bf16_f32 v148, v112, v113
	v_cvt_pk_bf16_f32 v149, v114, v115
	ds_read_b64_tr_b16 v[152:153], v4 offset:28672
	ds_read_b64_tr_b16 v[154:155], v4 offset:29184
	s_waitcnt lgkmcnt(6)
	v_mfma_f32_32x32x16_bf16 v[64:79], v[164:167], v[144:147], v[48:63]
	v_add_f32_e32 v2, v118, v2
	v_add_f32_e32 v2, v119, v2
	v_add_f32_e32 v2, v120, v2
	v_add_f32_e32 v2, v121, v2
	v_cvt_pk_bf16_f32 v150, v116, v117
	v_cvt_pk_bf16_f32 v151, v118, v119
	ds_read_b64_tr_b16 v[6:7], v4 offset:25600
	ds_read_b64_tr_b16 v[8:9], v4 offset:26112
	s_waitcnt lgkmcnt(7)
	v_mfma_f32_32x32x16_bf16 v[80:95], v[168:171], v[136:139], v[80:95]
	v_add_f32_e32 v2, v122, v2
	v_add_f32_e32 v2, v123, v2
	v_add_f32_e32 v2, v124, v2
	v_add_f32_e32 v2, v125, v2
	v_cvt_pk_bf16_f32 v140, v120, v121
	v_cvt_pk_bf16_f32 v141, v122, v123
	ds_read_b64_tr_b16 v[112:113], v4 offset:29696
	ds_read_b64_tr_b16 v[114:115], v4 offset:30208
	s_waitcnt lgkmcnt(8)
	v_mfma_f32_32x32x16_bf16 v[64:79], v[160:163], v[136:139], v[64:79]
	v_add_f32_e32 v2, v126, v2
	v_add_f32_e32 v2, v127, v2
	v_add_f32_e32 v2, v96, v2
	v_add_f32_e32 v2, v97, v2
	v_cvt_pk_bf16_f32 v142, v124, v125
	v_cvt_pk_bf16_f32 v143, v126, v127
	ds_read_b64_tr_b16 v[116:117], v4 offset:26624
	ds_read_b64_tr_b16 v[118:119], v4 offset:27136
	v_add_f32_e32 v2, v98, v2
	v_add_f32_e32 v2, v99, v2
	v_add_f32_e32 v2, v100, v2
	v_add_f32_e32 v2, v101, v2
	v_cvt_pk_bf16_f32 v132, v96, v97
	v_cvt_pk_bf16_f32 v133, v98, v99
	ds_read_b64_tr_b16 v[96:97], v4 offset:30720
	ds_read_b64_tr_b16 v[98:99], v4 offset:31232
	v_add_f32_e32 v2, v102, v2
	v_add_f32_e32 v2, v103, v2
	v_add_f32_e32 v2, v104, v2
	v_add_f32_e32 v2, v105, v2
	v_cvt_pk_bf16_f32 v134, v100, v101
	v_cvt_pk_bf16_f32 v135, v102, v103
	ds_read_b64_tr_b16 v[10:11], v4 offset:27648
	ds_read_b64_tr_b16 v[12:13], v4 offset:28160
	v_add_f32_e32 v2, v106, v2
	v_add_f32_e32 v2, v107, v2
	v_add_f32_e32 v2, v108, v2
	v_add_f32_e32 v15, v109, v2
	v_cvt_pk_bf16_f32 v128, v104, v105
	v_cvt_pk_bf16_f32 v129, v106, v107
	ds_read_b64_tr_b16 v[2:3], v4 offset:31744
	ds_read_b64_tr_b16 v[4:5], v4 offset:32256
	v_add_f32_e32 v15, v110, v15
	v_add_f32_e32 v15, v111, v15
	v_cvt_pk_bf16_f32 v130, v108, v109
	v_cvt_pk_bf16_f32 v131, v110, v111
	v_max_f32_e32 v100, v81, v81
	v_max_f32_e32 v101, v80, v80
	v_max_f32_e32 v100, v101, v100
	v_max3_f32 v101, v82, v83, v65
	v_max3_f32 v100, v100, v64, v66
	v_max3_f32 v100, v100, v67, v84
	v_max3_f32 v101, v101, v86, v87
	v_max3_f32 v100, v100, v85, v68
	v_max3_f32 v101, v101, v70, v71
	v_max3_f32 v100, v100, v69, v88
	v_max3_f32 v101, v101, v90, v91
	v_max3_f32 v100, v100, v89, v72
	v_max3_f32 v101, v101, v74, v75
	v_max3_f32 v100, v100, v73, v92
	v_max3_f32 v101, v101, v94, v95
	v_max3_f32 v100, v100, v93, v76
	v_max3_f32 v101, v101, v78, v79
	v_add_f32_e32 v196, v14, v15
	v_max3_f32 v14, v100, v77, v101
	v_mov_b32_e32 v15, v14
	s_nop 1
	v_permlane32_swap_b32_e32 v14, v15
	s_add_i32 s3, s16, s75
	s_mov_b32 s12, m0
	s_mov_b32 m0, s3
	s_nop 0
	global_load_lds_dwordx4 v[178:179], off
	s_mov_b32 m0, s12
	v_max_f32_e32 v14, v14, v15
	s_add_i32 s3, s78, s76
	s_mov_b32 s12, m0
	s_mov_b32 m0, s3
	s_nop 0
	global_load_lds_dwordx4 v[176:177], off
	s_mov_b32 m0, s12
	v_cmp_lt_f32_e32 vcc, s58, v14
	s_cmp_lg_u64 vcc, 0
	s_cselect_b64 s[12:13], -1, 0
	s_cbranch_vccnz .LBB0_574

; __device__ __forceinline__ unsigned xb_add(unsigned* p, unsigned v) { return __hip_atomic_fetch_add(p, v, __ATOMIC_RELAXED, __HIP_MEMORY_SCOPE_AGENT); }
; __device__ __forceinline__ void xcd_barrier(const XcdBarrier& b) {
;     asm volatile("s_waitcnt vmcnt(0)" ::: "memory");
;     __syncthreads();
;     if (threadIdx.x == 0) {
;         unsigned* bar = b.bar;
;         __builtin_amdgcn_s_waitcnt(0);
;         unsigned nloc = b.st[0], nx = b.st[1];
;         if (nloc == 0u) { xcd_barrier_complete(bar, b.x, nloc, nx); b.st[0] = nloc; b.st[1] = nx; }
;         const unsigned old = xb_add(&bar[XB_XSUB(b.x)], 1u);
;         const unsigned gen = old / nloc;
.LBB0_633:
	s_nop 0
	s_nop 0
	s_nop 0
	s_nop 0
	s_nop 0
	s_nop 0
	s_mov_b64 s[6:7], s[0:1]
	s_getreg_b32 s2, hwreg(HW_REG_XCC_ID, 0, 4)
	s_waitcnt vmcnt(0)
	s_barrier
	s_mov_b64 s[4:5], exec
	v_readlane_b32 s8, v255, 0
	v_readlane_b32 s9, v255, 1
	s_and_b64 s[8:9], s[4:5], s[8:9]
	v_readlane_b32 s41, v255, 10
	s_movk_i32 s42, 0x1000
	s_mov_b64 s[48:49], 0x1200
	s_mov_b32 s62, 0x3c800000
	s_mov_b64 exec, s[8:9]
	s_cbranch_execz .LBB0_685
	v_readlane_b32 s3, v255, 2
	s_load_dwordx2 s[6:7], s[6:7], 0x118
	s_waitcnt vmcnt(0) expcnt(0) lgkmcnt(0)
	v_mov_b32_e32 v0, s3
	ds_read_b32 v3, v0
	v_readlane_b32 s3, v255, 3
	s_and_b32 s2, s2, 15
	s_waitcnt lgkmcnt(0)
	v_cmp_ne_u32_e32 vcc, 0, v3
	v_mov_b32_e32 v0, s3
	ds_read_b32 v0, v0
	s_cbranch_vccnz .LBB0_649
	s_add_u32 s8, s6, 0x1000
	s_addc_u32 s9, s7, 0
	s_add_u32 s10, s6, 0x1100
	s_addc_u32 s11, s7, 0
	s_add_u32 s12, s6, 0x1200
	s_addc_u32 s13, s7, 0
	s_add_u32 s14, s6, 0x1300
	s_addc_u32 s15, s7, 0
	s_mov_b32 s3, 1
	s_branch .LBB0_637
